# v113 with s_nop 0 restored between the M0 write and the LDS-DMA load at 6 prologue sites (hazard-clean)
# baseline (speedup 1.0000x reference)
.LBB0_432:
	s_add_i32 m0, s17, 0x17f80
	v_lshl_add_u64 v[20:21], v[2:3], 0, v[132:133]
	s_waitcnt vmcnt(4)
	s_barrier
	global_load_lds_dwordx4 v[4:5], off offset:128
	s_add_i32 m0, s17, 0x19f80
	s_add_i32 s29, s17, 0x8000
	v_lshl_add_u64 v[22:23], v[2:3], 0, v[130:131]
	global_load_lds_dwordx4 v[6:7], off offset:128
	s_add_i32 m0, s29, 0xffffff80
	s_add_i32 s35, s17, 0xa000
	global_load_lds_dwordx4 v[20:21], off offset:128
	s_add_i32 m0, s35, 0xffffff80
	s_lshl_b32 s0, s0, 5
	global_load_lds_dwordx4 v[22:23], off offset:128
	s_add_i32 m0, s17, 0x1bf80
	s_nop 0
	global_load_lds_dwordx4 v[8:9], off offset:128
	s_add_i32 m0, s17, 0x1df80
	s_and_b32 s0, s0, 0x60
	global_load_lds_dwordx4 v[10:11], off offset:128
	v_bfe_u32 v4, v12, 4, 2
	v_and_b32_e32 v5, 15, v12
	v_lshlrev_b32_e32 v6, 4, v4
	v_lshl_or_b32 v1, s1, 6, v5
	v_lshl_or_b32 v5, v5, 6, v6
	v_lshlrev_b32_e32 v6, 2, v12
	s_lshl_b32 s1, s1, 13
	v_and_b32_e32 v6, 32, v6
	v_bitop3_b32 v8, v5, s1, v6 bitop3:0xde
	s_lshl_b32 s1, s0, 7
	v_bitop3_b32 v144, v5, s1, v6 bitop3:0xde
	v_add_u32_e32 v5, v16, v17
	s_waitcnt vmcnt(6)
	v_add_lshl_u32 v6, v5, v18, 1
	v_mov_b32_e32 v7, v0
	v_add_u32_e32 v5, v13, v14
	v_lshl_or_b32 v4, v4, 2, s0
	v_lshl_add_u64 v[134:135], s[94:95], 0, v[6:7]
	v_add_lshl_u32 v6, v5, v15, 1
	s_add_i32 s36, s13, -2
	s_ashr_i32 s42, s37, 31
	s_mov_b32 s25, s95
	v_lshl_add_u64 v[136:137], s[94:95], 0, v[6:7]
	s_mov_b32 s43, 0
	v_add_u32_e32 v145, 0, v8
	v_lshlrev_b32_e32 v138, 1, v4
	s_barrier
	s_waitcnt vmcnt(0)

.LBB0_452:
	v_mov_b32_e32 v131, v0
	s_add_i32 m0, s8, 0x17f80
	v_lshl_add_u64 v[20:21], v[2:3], 0, v[130:131]
	v_mov_b32_e32 v135, v0
	s_waitcnt vmcnt(4)
	s_barrier
	global_load_lds_dwordx4 v[4:5], off offset:128
	s_add_i32 m0, s8, 0x19f80
	s_add_i32 s12, s8, 0x8000
	v_lshl_add_u64 v[22:23], v[2:3], 0, v[134:135]
	global_load_lds_dwordx4 v[6:7], off offset:128
	s_add_i32 m0, s12, 0xffffff80
	s_add_i32 s22, s8, 0xa000
	global_load_lds_dwordx4 v[20:21], off offset:128
	s_add_i32 m0, s22, 0xffffff80
	v_and_b32_e32 v6, 15, v12
	global_load_lds_dwordx4 v[22:23], off offset:128
	s_add_i32 m0, s8, 0x1bf80
	s_nop 0
	global_load_lds_dwordx4 v[8:9], off offset:128
	s_add_i32 m0, s8, 0x1df80
	v_and_b32_e32 v8, 48, v12
	global_load_lds_dwordx4 v[10:11], off offset:128
	v_bfe_u32 v5, v12, 4, 2
	s_and_b32 s2, s0, 3
	v_lshl_or_b32 v1, s1, 6, v6
	v_lshlrev_b32_e32 v7, 3, v5
	v_lshl_or_b32 v6, v6, 6, v8
	v_lshlrev_b32_e32 v8, 2, v12
	s_lshl_b32 s0, s0, 11
	s_lshl_b32 s36, s16, 3
	s_lshl_b32 s1, s1, 13
	v_and_b32_e32 v8, 32, v8
	v_lshl_or_b32 v167, s2, 5, v7
	s_add_i32 s23, s0, 0
	s_ashr_i32 s0, s37, 31
	v_cvt_f32_u32_e32 v7, s36
	v_bitop3_b32 v9, v6, s1, v8 bitop3:0xde
	s_lshl_b32 s1, s2, 12
	v_writelane_b32 v255, s0, 27
	s_ashr_i32 s0, s14, 31
	v_and_b32_e32 v4, 63, v12
	v_bitop3_b32 v166, v6, s1, v8 bitop3:0xde
	v_writelane_b32 v255, s0, 28
	v_readlane_b32 s0, v250, 12
	v_lshlrev_b32_e32 v6, 2, v4
	v_cmp_gt_u32_e64 s[38:39], 16, v4
	v_lshlrev_b32_e32 v4, 2, v5
	v_mov_b32_e32 v5, v0
	v_readlane_b32 s1, v250, 13
	s_waitcnt vmcnt(6)
	s_add_i32 s23, s23, 0x22100
	s_add_i32 s28, s13, -2
	v_lshl_add_u64 v[138:139], s[0:1], 0, v[4:5]
	v_rcp_iflag_f32_e32 v4, v7
	s_lshr_b32 s0, s24, 3
	v_writelane_b32 v255, s0, 25
	s_lshl_b32 s0, s2, 3
	v_mul_f32_e32 v4, 0x4f7ffffe, v4
	v_cvt_u32_f32_e32 v4, v4
	s_add_i32 s45, s0, 0
	s_sub_i32 s0, 0, s36
	v_lshlrev_b32_e32 v168, 5, v1
	v_readfirstlane_b32 s1, v4
	v_add_u32_e32 v4, v15, v13
	s_mul_i32 s0, s0, s1
	v_add_lshl_u32 v4, v4, v14, 1
	s_mul_hi_u32 s0, s1, s0
	v_lshl_add_u64 v[140:141], s[94:95], 0, v[4:5]
	v_add_u32_e32 v4, v18, v16
	s_add_i32 s0, s1, s0
	v_add_lshl_u32 v4, v4, v17, 1
	s_mov_b32 s25, s95
	s_add_i32 s45, s45, 0x20000
	s_mov_b32 s54, 0
	v_writelane_b32 v255, s0, 33
	v_lshl_add_u64 v[142:143], s[94:95], 0, v[4:5]
	s_add_i32 s91, s23, 0x300
	s_add_i32 s2, s23, 0x500
	s_add_i32 s44, s23, 0x700
	v_add_u32_e32 v169, 0, v9
	v_add_u32_e32 v170, s23, v6
	s_mov_b32 s89, 0xff61b1e6
	s_barrier
	s_branch .LBB0_454

.LBB0_509:
	v_readlane_b32 s68, v253, 7
	v_writelane_b32 v255, s38, 29
	s_lshl_b64 s[6:7], s[38:39], 2
	v_readlane_b32 s78, v253, 17
	v_readlane_b32 s69, v253, 8
	v_readlane_b32 s79, v253, 18
	s_add_u32 s68, s78, s6
	v_readlane_b32 s70, v253, 9
	v_readlane_b32 s82, v253, 21
	s_addc_u32 s69, s79, s7
	v_readlane_b32 s71, v253, 10
	v_readlane_b32 s83, v253, 22
	s_add_u32 s70, s82, s6
	v_mov_b32_e32 v141, v0
	s_addc_u32 s71, s83, s7
	s_add_i32 m0, s12, 0x17f80
	v_lshl_add_u64 v[18:19], v[2:3], 0, v[140:141]
	v_mov_b32_e32 v145, v0
	s_waitcnt vmcnt(4)
	s_barrier
	global_load_lds_dwordx4 v[4:5], off offset:128
	s_add_i32 m0, s12, 0x19f80
	s_add_i32 s54, s12, 0x8000
	v_lshl_add_u64 v[20:21], v[2:3], 0, v[144:145]
	global_load_lds_dwordx4 v[6:7], off offset:128
	s_add_i32 m0, s54, 0xffffff80
	s_add_i32 s2, s12, 0xa000
	global_load_lds_dwordx4 v[18:19], off offset:128
	s_add_i32 m0, s2, 0xffffff80
	s_lshl_b32 s0, s0, 5
	global_load_lds_dwordx4 v[20:21], off offset:128
	s_add_i32 m0, s12, 0x1bf80
	s_nop 0
	global_load_lds_dwordx4 v[8:9], off offset:128
	s_add_i32 m0, s12, 0x1df80
	s_and_b32 s0, s0, 0x60
	global_load_lds_dwordx4 v[10:11], off offset:128
	v_lshrrev_b32_e32 v5, 1, v1
	v_and_b32_e32 v5, 24, v5
	v_and_b32_e32 v4, 15, v1
	v_lshlrev_b32_e32 v6, 1, v5
	v_lshlrev_b32_e32 v1, 2, v1
	v_lshl_or_b32 v166, s1, 6, v4
	v_lshl_or_b32 v4, v4, 6, v6
	s_lshl_b32 s1, s1, 13
	v_and_b32_e32 v1, 32, v1
	v_bitop3_b32 v6, v4, s1, v1 bitop3:0xde
	s_lshl_b32 s1, s0, 7
	s_lshl_b32 s22, s16, 3
	v_bitop3_b32 v167, v4, s1, v1 bitop3:0xde
	v_cvt_f32_u32_e32 v1, s22
	v_or_b32_e32 v148, s0, v5
	s_sub_i32 s0, 0, s22
	s_waitcnt vmcnt(6)
	v_rcp_iflag_f32_e32 v1, v1
	v_mov_b32_e32 v5, v0
	v_readlane_b32 s72, v253, 11
	v_readlane_b32 s73, v253, 12
	v_mul_f32_e32 v1, 0x4f7ffffe, v1
	v_cvt_u32_f32_e32 v1, v1
	v_readlane_b32 s52, v250, 49
	v_writelane_b32 v255, s39, 30
	s_mov_b32 s65, s16
	v_readfirstlane_b32 s1, v1
	v_add_u32_e32 v1, v14, v12
	s_mul_i32 s0, s0, s1
	v_add_lshl_u32 v4, v1, v13, 1
	v_add_u32_e32 v1, v17, v15
	s_mul_hi_u32 s0, s1, s0
	v_lshl_add_u64 v[150:151], s[94:95], 0, v[4:5]
	v_add_lshl_u32 v4, v1, v16, 1
	s_add_i32 s23, s13, -2
	s_ashr_i32 s28, s37, 31
	s_ashr_i32 s29, s14, 31
	s_mov_b32 s25, s95
	s_lshr_b32 s72, s24, 3
	s_mov_b32 s90, 0
	s_add_i32 s73, s1, s0
	v_mov_b32_e32 v149, v0
	v_lshl_add_u64 v[152:153], s[94:95], 0, v[4:5]
	v_add_u32_e32 v168, 0, v6
	s_movk_i32 s89, 0x900
	v_readlane_b32 s53, v250, 50
	s_mov_b32 s16, 0xbf1b459e
	v_readlane_b32 s74, v253, 13
	v_readlane_b32 s75, v253, 14
	v_readlane_b32 s76, v253, 15
	v_readlane_b32 s77, v253, 16
	v_readlane_b32 s80, v253, 19
	v_readlane_b32 s81, v253, 20
	s_barrier
	s_branch .LBB0_512

.LBB0_640:
	s_cmp_eq_u32 s97, 0
	v_mov_b32_e32 v161, v0
	s_cselect_b64 vcc, -1, 0
	s_add_i32 m0, s8, 0x17f80
	v_lshl_add_u64 v[20:21], v[2:3], 0, v[160:161]
	v_mov_b32_e32 v165, v0
	s_waitcnt vmcnt(4)
	s_barrier
	global_load_lds_dwordx4 v[4:5], off offset:128
	s_add_i32 m0, s8, 0x19f80
	s_add_i32 s12, s8, 0x8000
	v_lshl_add_u64 v[22:23], v[2:3], 0, v[164:165]
	global_load_lds_dwordx4 v[6:7], off offset:128
	s_add_i32 m0, s12, 0xffffff80
	s_add_i32 s28, s8, 0xa000
	global_load_lds_dwordx4 v[20:21], off offset:128
	s_add_i32 m0, s28, 0xffffff80
	s_and_b32 s0, s0, 3
	global_load_lds_dwordx4 v[22:23], off offset:128
	s_add_i32 m0, s8, 0x1bf80
	s_nop 0
	global_load_lds_dwordx4 v[8:9], off offset:128
	s_add_i32 m0, s8, 0x1df80
	v_lshlrev_b32_e32 v8, 2, v12
	global_load_lds_dwordx4 v[10:11], off offset:128
	v_bfe_u32 v4, v12, 4, 2
	v_and_b32_e32 v5, 15, v12
	v_lshlrev_b32_e32 v7, 4, v4
	s_lshl_b32 s2, s1, 6
	v_lshl_or_b32 v7, v5, 6, v7
	s_lshl_b32 s1, s1, 13
	v_and_b32_e32 v8, 32, v8
	v_bitop3_b32 v9, v7, s1, v8 bitop3:0xde
	s_lshl_b32 s1, s0, 12
	v_bitop3_b32 v237, v7, s1, v8 bitop3:0xde
	s_add_i32 s1, s2, 0x80
	v_lshlrev_b32_e32 v6, 3, v4
	v_cmp_eq_u32_e64 s[38:39], 0, v4
	v_or_b32_e32 v4, s1, v5
	v_lshlrev_b32_e32 v240, 4, v4
	v_lshl_or_b32 v4, s0, 4, v5
	s_lshl_b32 s44, s16, 3
	v_or_b32_e32 v241, s2, v4
	v_cvt_f32_u32_e32 v4, s44
	v_mov_b32_e32 v1, s36
	v_lshl_or_b32 v238, s0, 5, v6
	s_lshl_b32 s0, s0, 2
	v_rcp_iflag_f32_e32 v4, v4
	v_cndmask_b32_e32 v168, 0, v1, vcc
	v_or_b32_e32 v1, s2, v5
	s_add_i32 s90, s0, 0
	v_mul_f32_e32 v4, 0x4f7ffffe, v4
	v_cvt_u32_f32_e32 v4, v4
	s_sub_i32 s0, 0, s44
	v_mov_b32_e32 v5, v0
	s_waitcnt vmcnt(6)
	v_readfirstlane_b32 s1, v4
	v_add_u32_e32 v4, v15, v13
	v_add_lshl_u32 v4, v4, v14, 1
	s_mul_i32 s0, s0, s1
	v_lshl_add_u64 v[172:173], s[94:95], 0, v[4:5]
	v_add_u32_e32 v4, v18, v16
	s_mul_hi_u32 s0, s1, s0
	v_add_lshl_u32 v4, v4, v17, 1
	s_mov_b32 s29, 0
	s_add_i32 s35, s13, -2
	v_lshlrev_b32_e32 v239, 4, v1
	v_add_u32_e32 v242, 0x80, v241
	s_ashr_i32 s36, s37, 31
	s_ashr_i32 s45, s14, 31
	s_mov_b32 s25, s95
	s_lshr_b32 s54, s24, 3
	v_mov_b32_e32 v170, v168
	v_mov_b32_e32 v171, v168
	s_add_i32 s90, s90, 0x20000
	s_add_i32 s91, s1, s0
	v_lshl_add_u64 v[174:175], s[94:95], 0, v[4:5]
	v_add_u32_e32 v243, 0, v9
	s_barrier
	s_branch .LBB0_642

.LBB0_679:
	s_lshl_b64 s[6:7], s[38:39], 2
	v_readlane_b32 s22, v250, 19
	v_readlane_b32 s23, v250, 20
	s_add_u32 s6, s22, s6
	v_mov_b32_e32 v147, v0
	s_addc_u32 s7, s23, s7
	s_add_i32 m0, s10, 0x17f80
	v_lshl_add_u64 v[20:21], v[2:3], 0, v[146:147]
	v_mov_b32_e32 v151, v0
	s_waitcnt vmcnt(4)
	s_barrier
	global_load_lds_dwordx4 v[4:5], off offset:128
	s_add_i32 m0, s10, 0x19f80
	s_add_i32 s54, s10, 0x8000
	v_lshl_add_u64 v[22:23], v[2:3], 0, v[150:151]
	global_load_lds_dwordx4 v[6:7], off offset:128
	s_add_i32 m0, s54, 0xffffff80
	s_add_i32 s3, s10, 0xa000
	global_load_lds_dwordx4 v[20:21], off offset:128
	s_add_i32 m0, s3, 0xffffff80
	v_and_b32_e32 v6, 15, v12
	global_load_lds_dwordx4 v[22:23], off offset:128
	s_add_i32 m0, s10, 0x1bf80
	s_nop 0
	global_load_lds_dwordx4 v[8:9], off offset:128
	s_add_i32 m0, s10, 0x1df80
	v_and_b32_e32 v7, 48, v12
	global_load_lds_dwordx4 v[10:11], off offset:128
	v_lshl_or_b32 v1, s0, 6, v6
	v_lshl_or_b32 v6, v6, 6, v7
	v_lshlrev_b32_e32 v7, 2, v12
	s_lshl_b32 s0, s0, 13
	v_and_b32_e32 v7, 32, v7
	v_bitop3_b32 v8, v6, s0, v7 bitop3:0xde
	s_lshl_b32 s0, s1, 5
	s_lshl_b32 s1, s1, 11
	v_writelane_b32 v255, s6, 25
	s_and_b32 s0, s0, 0x60
	s_add_i32 s35, s1, 0
	v_writelane_b32 v255, s7, 26
	s_lshl_b32 s6, s0, 7
	s_add_i32 s35, s35, 0x22100
	s_add_i32 s44, s13, -2
	s_ashr_i32 s65, s37, 31
	s_ashr_i32 s96, s14, 31
	s_cmp_lg_u64 s[28:29], 0
	s_cselect_b64 s[42:43], -1, 0
	s_lshl_b32 s45, s16, 3
	v_bitop3_b32 v176, s6, v6, v7 bitop3:0xf6
	v_cvt_f32_u32_e32 v6, s45
	v_and_b32_e32 v4, 63, v12
	v_bfe_u32 v5, v12, 4, 2
	v_lshlrev_b32_e32 v7, 2, v4
	v_rcp_iflag_f32_e32 v6, v6
	v_lshl_or_b32 v177, v5, 3, s0
	v_lshlrev_b32_e32 v4, 2, v5
	v_mov_b32_e32 v5, v0
	v_lshl_add_u64 v[154:155], s[28:29], 0, v[4:5]
	v_mul_f32_e32 v4, 0x4f7ffffe, v6
	v_cvt_u32_f32_e32 v4, v4
	s_lshr_b32 s0, s24, 3
	v_writelane_b32 v255, s0, 27
	s_sub_i32 s0, 0, s45
	v_readfirstlane_b32 s1, v4
	v_add_u32_e32 v4, v15, v13
	s_mul_i32 s0, s0, s1
	v_add_lshl_u32 v4, v4, v14, 1
	s_waitcnt vmcnt(6)
	s_mul_hi_u32 s0, s1, s0
	v_lshl_add_u64 v[156:157], s[94:95], 0, v[4:5]
	v_add_u32_e32 v4, v18, v16
	s_add_i32 s0, s1, s0
	v_add_lshl_u32 v4, v4, v17, 1
	s_mov_b32 s25, s95
	s_mov_b32 s12, 0
	v_writelane_b32 v255, s0, 28
	v_lshl_add_u64 v[160:161], s[94:95], 0, v[4:5]
	v_add_u32_e32 v178, 0, v8
	v_add_u32_e32 v179, s35, v7
	s_mov_b64 s[90:91], s[42:43]
	s_barrier
	s_branch .LBB0_682

.LBB0_814:
	v_mov_b32_e32 v137, v0
	s_add_i32 m0, s28, 0x17f80
	v_lshl_add_u64 v[20:21], v[2:3], 0, v[136:137]
	v_mov_b32_e32 v133, v0
	s_waitcnt vmcnt(4)
	s_barrier
	global_load_lds_dwordx4 v[4:5], off offset:128
	s_add_i32 m0, s28, 0x19f80
	s_add_i32 s36, s28, 0x8000
	v_lshl_add_u64 v[22:23], v[2:3], 0, v[132:133]
	global_load_lds_dwordx4 v[6:7], off offset:128
	s_add_i32 m0, s36, 0xffffff80
	s_add_i32 s42, s28, 0xa000
	global_load_lds_dwordx4 v[20:21], off offset:128
	s_add_i32 m0, s42, 0xffffff80
	v_bfe_u32 v7, v12, 4, 2
	global_load_lds_dwordx4 v[22:23], off offset:128
	s_add_i32 m0, s28, 0x1bf80
	s_nop 0
	global_load_lds_dwordx4 v[8:9], off offset:128
	s_add_i32 m0, s28, 0x1df80
	v_and_b32_e32 v6, 63, v12
	global_load_lds_dwordx4 v[10:11], off offset:128
	v_and_b32_e32 v4, 15, v12
	v_and_b32_e32 v5, 48, v12
	v_lshl_or_b32 v1, s1, 6, v4
	v_lshl_or_b32 v4, v4, 6, v5
	v_lshlrev_b32_e32 v5, 2, v12
	s_lshl_b32 s1, s1, 13
	v_and_b32_e32 v5, 32, v5
	v_bitop3_b32 v8, v4, s1, v5 bitop3:0xde
	s_lshl_b32 s1, s0, 5
	s_and_b32 s1, s1, 0x60
	s_lshl_b32 s6, s1, 7
	v_bitop3_b32 v153, s6, v4, v5 bitop3:0xf6
	v_readlane_b32 s6, v250, 12
	v_lshlrev_b32_e32 v4, 2, v7
	v_mov_b32_e32 v5, v0
	v_readlane_b32 s7, v250, 13
	s_lshl_b32 s0, s0, 11
	s_waitcnt vmcnt(6)
	s_add_i32 s43, s0, 0
	v_lshl_add_u64 v[138:139], s[6:7], 0, v[4:5]
	v_add_u32_e32 v4, v18, v16
	v_add_lshl_u32 v4, v4, v17, 1
	v_lshl_add_u64 v[140:141], s[94:95], 0, v[4:5]
	v_add_u32_e32 v4, v15, v13
	s_add_i32 s43, s43, 0x22100
	v_lshlrev_b32_e32 v6, 2, v6
	v_add_lshl_u32 v4, v4, v14, 1
	s_add_i32 s44, s13, -2
	s_ashr_i32 s45, s37, 31
	s_mov_b32 s25, s95
	v_lshl_or_b32 v155, v7, 3, s1
	v_lshl_add_u64 v[142:143], s[94:95], 0, v[4:5]
	s_mov_b32 s54, 0
	v_add_u32_e32 v157, 0, v8
	v_add_u32_e32 v161, s43, v6
	s_movk_i32 s89, 0x1600
	s_barrier
